# stack on v41: scan DPP prefix sums + C-tile swizzle, SSD conv weights in LDS + cross-iteration prefetch, cq loop rewrite, no score-wave priority
# speedup vs baseline: 1.0047x; 1.0031x over previous
.Lswz_e7:
	s_waitcnt vmcnt(1)
	ds_write_b128 v2, v[18:21] offset:17408
	s_waitcnt vmcnt(0)
	ds_write_b128 v6, v[22:25] offset:45056
	s_cbranch_vccnz .LBB0_97
	v_mul_f32_e64 v2, v126, -v0
	s_nop 1
	v_add_f32_dpp v2, v2, v2 row_shr:1 row_mask:0xf bank_mask:0xf
	s_nop 1
	v_add_f32_dpp v2, v2, v2 row_shr:2 row_mask:0xf bank_mask:0xf
	s_nop 1
	v_add_f32_dpp v2, v2, v2 row_shr:4 row_mask:0xf bank_mask:0xf
	s_nop 1
	v_add_f32_dpp v2, v2, v2 row_shr:8 row_mask:0xf bank_mask:0xf
	s_nop 1
	v_add_f32_dpp v2, v2, v2 row_bcast:15 row_mask:0xa bank_mask:0xf
	s_nop 1
	v_add_f32_dpp v2, v2, v2 row_bcast:31 row_mask:0xc bank_mask:0xf
	s_nop 1
	v_readlane_b32 s74, v2, 63
	s_nop 1
	v_sub_f32_e32 v3, s74, v2
	v_mul_f32_e32 v3, 0x3fb8aa3b, v3
	v_exp_f32_e32 v3, v3
	s_nop 0
	v_mul_f32_e32 v3, v126, v3
	ds_write2st64_b32 v104, v2, v3 offset0:212 offset1:214

.Lswz_e5:
	v_add_u32_e32 v2, v110, v109
	s_and_b64 vcc, exec, s[16:17]
	s_waitcnt vmcnt(1)
	ds_write_b128 v2, v[18:21]
	s_waitcnt vmcnt(0)
	ds_write_b128 v124, v[22:25] offset:9216
	s_cbranch_vccnz .LBB0_102
	v_mul_f32_e64 v2, v126, -v0
	s_nop 1
	v_add_f32_dpp v2, v2, v2 row_shr:1 row_mask:0xf bank_mask:0xf
	s_nop 1
	v_add_f32_dpp v2, v2, v2 row_shr:2 row_mask:0xf bank_mask:0xf
	s_nop 1
	v_add_f32_dpp v2, v2, v2 row_shr:4 row_mask:0xf bank_mask:0xf
	s_nop 1
	v_add_f32_dpp v2, v2, v2 row_shr:8 row_mask:0xf bank_mask:0xf
	s_nop 1
	v_add_f32_dpp v2, v2, v2 row_bcast:15 row_mask:0xa bank_mask:0xf
	s_nop 1
	v_add_f32_dpp v2, v2, v2 row_bcast:31 row_mask:0xc bank_mask:0xf
	s_nop 1
	v_readlane_b32 s74, v2, 63
	s_nop 1
	v_sub_f32_e32 v3, s74, v2
	v_mul_f32_e32 v3, 0x3fb8aa3b, v3
	v_exp_f32_e32 v3, v3
	s_nop 0
	v_mul_f32_e32 v3, v126, v3
	ds_write2st64_b32 v111, v2, v3 offset1:2

.Lswz_e3:
	v_add_u32_e32 v58, v59, v109
	s_and_b64 vcc, exec, s[16:17]
	s_waitcnt vmcnt(15)
	ds_write_b128 v58, v[18:21] offset:17408
	s_waitcnt vmcnt(14)
	ds_write_b128 v60, v[22:25] offset:45056
	s_cbranch_vccnz .LBB0_108
	v_mul_f32_e64 v58, v126, -v0
	s_nop 1
	v_add_f32_dpp v58, v58, v58 row_shr:1 row_mask:0xf bank_mask:0xf
	s_nop 1
	v_add_f32_dpp v58, v58, v58 row_shr:2 row_mask:0xf bank_mask:0xf
	s_nop 1
	v_add_f32_dpp v58, v58, v58 row_shr:4 row_mask:0xf bank_mask:0xf
	s_nop 1
	v_add_f32_dpp v58, v58, v58 row_shr:8 row_mask:0xf bank_mask:0xf
	s_nop 1
	v_add_f32_dpp v58, v58, v58 row_bcast:15 row_mask:0xa bank_mask:0xf
	s_nop 1
	v_add_f32_dpp v58, v58, v58 row_bcast:31 row_mask:0xc bank_mask:0xf
	s_nop 1
	v_readlane_b32 s74, v58, 63
	s_add_i32 s19, s19, s50
	v_lshl_add_u32 v60, v158, 2, s19
	s_nop 1
	v_sub_f32_e32 v59, s74, v58
	v_mul_f32_e32 v59, 0x3fb8aa3b, v59
	v_exp_f32_e32 v59, v59
	s_nop 0
	v_mul_f32_e32 v59, v126, v59
	ds_write2st64_b32 v60, v58, v59 offset0:212 offset1:214

.Lswz_e1:
	v_add_u32_e32 v58, v59, v109
	s_and_b64 vcc, exec, s[16:17]
	s_waitcnt vmcnt(15)
	ds_write_b128 v58, v[236:239] offset:17408
	s_waitcnt vmcnt(14)
	ds_write_b128 v60, v[240:243] offset:45056
	s_cbranch_vccnz .Lscan_B108
	v_mul_f32_e64 v58, v244, -v0
	s_nop 1
	v_add_f32_dpp v58, v58, v58 row_shr:1 row_mask:0xf bank_mask:0xf
	s_nop 1
	v_add_f32_dpp v58, v58, v58 row_shr:2 row_mask:0xf bank_mask:0xf
	s_nop 1
	v_add_f32_dpp v58, v58, v58 row_shr:4 row_mask:0xf bank_mask:0xf
	s_nop 1
	v_add_f32_dpp v58, v58, v58 row_shr:8 row_mask:0xf bank_mask:0xf
	s_nop 1
	v_add_f32_dpp v58, v58, v58 row_bcast:15 row_mask:0xa bank_mask:0xf
	s_nop 1
	v_add_f32_dpp v58, v58, v58 row_bcast:31 row_mask:0xc bank_mask:0xf
	s_nop 1
	v_readlane_b32 s74, v58, 63
	s_add_i32 s19, s19, s50
	v_lshl_add_u32 v60, v158, 2, s19
	s_nop 1
	v_sub_f32_e32 v59, s74, v58
	v_mul_f32_e32 v59, 0x3fb8aa3b, v59
	v_exp_f32_e32 v59, v59
	s_nop 0
	v_mul_f32_e32 v59, v244, v59
	ds_write2st64_b32 v60, v58, v59 offset0:212 offset1:214

.LBB0_405:
	v_add_u32_e32 v0, s29, v219
	v_mov_b64_e32 v[2:3], s[6:7]
	s_movk_i32 s8, 0x2800
	v_mad_i64_i32 v[2:3], s[8:9], v0, s8, v[2:3]
	v_or_b32_e32 v0, s28, v161
	v_mul_u32_u24_e32 v0, 0x140, v0
	v_lshlrev_b32_e32 v0, 1, v0
	v_lshl_add_u64 v[32:33], v[2:3], 0, v[0:1]
	s_setprio 0
	v_mov_b32_e32 v165, v1
	v_lshl_add_u64 v[32:33], v[32:33], 0, v[164:165]
	global_load_dwordx4 v[34:37], v[32:33], off
	global_load_dwordx4 v[38:41], v[32:33], off offset:32
	global_load_dwordx4 v[42:45], v[32:33], off offset:64
	global_load_dwordx4 v[46:49], v[32:33], off offset:96
	global_load_dwordx4 v[50:53], v[32:33], off offset:128
	global_load_dwordx4 v[54:57], v[32:33], off offset:160
	global_load_dwordx4 v[58:61], v[32:33], off offset:192
	global_load_dwordx4 v[62:65], v[32:33], off offset:224
	global_load_dwordx4 v[66:69], v[32:33], off offset:256
	global_load_dwordx4 v[70:73], v[32:33], off offset:288
	global_load_dwordx4 v[74:77], v[32:33], off offset:320
	global_load_dwordx4 v[78:81], v[32:33], off offset:352
	global_load_dwordx4 v[82:85], v[32:33], off offset:384
	global_load_dwordx4 v[86:89], v[32:33], off offset:416
	global_load_dwordx4 v[90:93], v[32:33], off offset:448
	global_load_dwordx4 v[94:97], v[32:33], off offset:480
	global_load_dwordx4 v[98:101], v[32:33], off offset:512
	global_load_dwordx4 v[102:105], v[32:33], off offset:544
	global_load_dwordx4 v[106:109], v[32:33], off offset:576
	global_load_dwordx4 v[110:113], v[32:33], off offset:608
	s_cmp_gt_i32 s27, 1
	s_cselect_b32 s8, 0xa000, 0
	s_add_u32 s8, s16, s8
	s_addc_u32 s9, s17, 0
	s_cmp_lt_i32 s27, 0
	v_mov_b32_e32 v0, 0
	s_waitcnt lgkmcnt(0)
	s_barrier
	s_cbranch_scc1 .LBB0_416
	s_mov_b64 s[8:9], 0x14090
	s_mov_b32 s18, 1
	s_add_i32 s19, s27, 1
	v_mov_b32_e32 v165, 0xf149f2ca
	v_mov_b32_e32 v0, 0
	s_mov_b32 s28, 0
	s_mov_b32 s29, 0
	s_mov_b32 s8, 0
	s_add_i32 s30, s8, 1
	s_cmp_ge_i32 s30, s27
	s_cbranch_scc1 .LBB0_409
